# v_d1 + P0 stores (transposed weights, bf16 x rows) write-through sc1 so the split-seam L2 writeback has little dirty data
# baseline (speedup 1.0000x reference)
.LBB0_172:
	s_waitcnt vmcnt(0)
	v_pk_mul_f32 v[2:3], v[2:3], v[6:7] op_sel_hi:[1,0]
	v_add_u32_e32 v7, 0x14a0, v70
	ds_write2_b32 v7, v2, v3 offset1:1
	v_pk_mul_f32 v[2:3], v[4:5], v[6:7] op_sel_hi:[1,0]
	v_add_u32_e32 v4, 0x14a8, v70
	ds_write2_b32 v4, v2, v3 offset1:1
	s_waitcnt lgkmcnt(0)
	ds_read2_b32 v[6:7], v57 offset0:33 offset1:41
	ds_read2_b32 v[8:9], v57 offset1:8
	ds_read2_b32 v[10:11], v57 offset0:66 offset1:74
	ds_read2_b32 v[12:13], v57 offset0:99 offset1:107
	ds_read2_b32 v[44:45], v57 offset0:132 offset1:140
	ds_read2_b32 v[70:71], v57 offset0:165 offset1:173
	ds_read2_b32 v[72:73], v57 offset0:198 offset1:206
	ds_read2_b32 v[74:75], v57 offset0:231 offset1:239
	s_waitcnt lgkmcnt(6)
	v_cvt_pk_bf16_f32 v2, v8, v6
	v_mul_lo_u32 v6, v69, s73
	v_add3_u32 v76, v14, v60, v6
	v_ashrrev_i32_e32 v77, 31, v76
	v_lshl_add_u64 v[42:43], v[42:43], 1, v[26:27]
	v_lshlrev_b64 v[78:79], 11, v[76:77]
	s_waitcnt lgkmcnt(4)
	v_cvt_pk_bf16_f32 v3, v10, v12
	s_waitcnt lgkmcnt(2)
	v_cvt_pk_bf16_f32 v4, v44, v70
	s_waitcnt lgkmcnt(0)
	v_cvt_pk_bf16_f32 v5, v72, v74
	v_lshl_add_u64 v[78:79], v[42:43], 0, v[78:79]
	v_add_u32_e32 v6, 8, v76
	global_store_dwordx4 v[78:79], v[2:5], off sc1
	s_nop 1
	v_cvt_pk_bf16_f32 v2, v9, v7
	v_ashrrev_i32_e32 v7, 31, v6
	v_cvt_pk_bf16_f32 v3, v11, v13
	v_cvt_pk_bf16_f32 v4, v45, v71
	v_cvt_pk_bf16_f32 v5, v73, v75
	v_lshlrev_b64 v[6:7], 11, v[6:7]
	ds_read2_b32 v[8:9], v57 offset0:49 offset1:57
	ds_read2_b32 v[10:11], v57 offset0:16 offset1:24
	ds_read2_b32 v[12:13], v57 offset0:82 offset1:90
	ds_read2_b32 v[44:45], v57 offset0:115 offset1:123
	ds_read2_b32 v[70:71], v57 offset0:148 offset1:156
	ds_read2_b32 v[72:73], v57 offset0:181 offset1:189
	ds_read2_b32 v[74:75], v57 offset0:214 offset1:222
	ds_read2_b32 v[78:79], v57 offset0:247 offset1:255
	v_lshl_add_u64 v[6:7], v[42:43], 0, v[6:7]
	global_store_dwordx4 v[6:7], v[2:5], off sc1
	v_add_u32_e32 v6, 16, v76
	v_ashrrev_i32_e32 v7, 31, v6
	v_lshlrev_b64 v[6:7], 11, v[6:7]
	s_waitcnt lgkmcnt(6)
	v_cvt_pk_bf16_f32 v2, v10, v8
	s_waitcnt lgkmcnt(4)
	v_cvt_pk_bf16_f32 v3, v12, v44
	s_waitcnt lgkmcnt(2)
	v_cvt_pk_bf16_f32 v4, v70, v72
	s_waitcnt lgkmcnt(0)
	v_cvt_pk_bf16_f32 v5, v74, v78
	v_lshl_add_u64 v[6:7], v[42:43], 0, v[6:7]
	global_store_dwordx4 v[6:7], v[2:5], off sc1
	v_add_u32_e32 v6, 24, v76
	v_ashrrev_i32_e32 v7, 31, v6
	v_lshlrev_b64 v[6:7], 11, v[6:7]
	v_cvt_pk_bf16_f32 v2, v11, v9
	v_cvt_pk_bf16_f32 v3, v13, v45
	v_cvt_pk_bf16_f32 v4, v71, v73
	v_cvt_pk_bf16_f32 v5, v75, v79
	v_lshl_add_u64 v[6:7], v[42:43], 0, v[6:7]
	global_store_dwordx4 v[6:7], v[2:5], off sc1
	s_waitcnt lgkmcnt(0)

.LBB0_174:
	v_cmp_lt_i32_e32 vcc, s5, v40
	s_and_saveexec_b64 s[8:9], vcc
	s_xor_b64 s[52:53], exec, s[8:9]
	s_cbranch_execz .LBB0_224
	v_cmp_lt_u32_e32 vcc, s33, v40
	s_and_saveexec_b64 s[8:9], vcc
	s_xor_b64 s[54:55], exec, s[8:9]
	s_cbranch_execz .LBB0_205
	v_cmp_lt_u32_e32 vcc, s60, v40
	s_and_saveexec_b64 s[8:9], vcc
	s_xor_b64 s[64:65], exec, s[8:9]
	s_cbranch_execz .LBB0_202
	v_cmp_lt_u32_e32 vcc, s61, v40
	s_and_saveexec_b64 s[8:9], vcc
	s_xor_b64 s[66:67], exec, s[8:9]
	s_cbranch_execz .LBB0_199
	v_cmp_lt_u32_e32 vcc, s62, v40
	s_and_saveexec_b64 s[8:9], vcc
	s_xor_b64 s[8:9], exec, s[8:9]
	s_cbranch_execz .LBB0_180
	v_and_b32_e32 v69, 0x1ffc0, v61
	v_and_b32_e32 v96, 0x3e0, v60
	v_lshlrev_b32_e32 v18, 2, v96
	v_or_b32_e32 v2, v69, v14
	v_lshl_add_u64 v[82:83], v[28:29], 0, v[18:19]
	v_lshlrev_b32_e32 v18, 12, v2
	v_or_b32_e32 v4, v69, v47
	v_lshl_add_u64 v[2:3], v[82:83], 0, v[18:19]
	v_lshlrev_b32_e32 v18, 12, v4
	v_or_b32_e32 v10, v69, v49
	v_lshl_add_u64 v[6:7], v[82:83], 0, v[18:19]
	v_lshlrev_b32_e32 v18, 12, v10
	v_or_b32_e32 v12, v69, v51
	v_lshl_add_u64 v[10:11], v[82:83], 0, v[18:19]
	v_lshlrev_b32_e32 v18, 12, v12
	v_lshl_add_u64 v[42:43], v[82:83], 0, v[18:19]
	v_or_b32_e32 v18, v69, v52
	v_lshlrev_b32_e32 v18, 12, v18
	v_lshl_add_u64 v[70:71], v[82:83], 0, v[18:19]
	v_or_b32_e32 v18, v69, v53
	v_lshlrev_b32_e32 v18, 12, v18
	v_lshl_add_u64 v[74:75], v[82:83], 0, v[18:19]
	global_load_dwordx4 v[2:5], v[2:3], off nt
	s_nop 0
	global_load_dwordx4 v[6:9], v[6:7], off nt
	s_nop 0
	global_load_dwordx4 v[10:13], v[10:11], off nt
	s_nop 0
	global_load_dwordx4 v[42:45], v[42:43], off nt
	s_nop 0
	global_load_dwordx4 v[70:73], v[70:71], off nt
	s_nop 0
	global_load_dwordx4 v[74:77], v[74:75], off nt
	v_or_b32_e32 v18, v69, v54
	v_lshlrev_b32_e32 v18, 12, v18
	v_lshl_add_u64 v[78:79], v[82:83], 0, v[18:19]
	v_or_b32_e32 v18, v69, v55
	global_load_dwordx4 v[78:81], v[78:79], off nt
	v_lshlrev_b32_e32 v18, 12, v18
	v_lshl_add_u64 v[82:83], v[82:83], 0, v[18:19]
	global_load_dwordx4 v[82:85], v[82:83], off nt
	v_add_u32_e32 v92, 0x1080, v62
	v_add_u32_e32 v93, 0x1088, v62
	v_add_u32_e32 v94, 0x14a0, v62
	v_add_u32_e32 v95, 0x14a8, v62
	v_add_u32_e32 v97, 0x18c0, v62
	v_add_u32_e32 v98, 0x18c8, v62
	v_add_u32_e32 v99, 0x1ce0, v62
	v_add_u32_e32 v100, 0x1ce8, v62
	v_or_b32_e32 v88, v96, v14
	v_lshlrev_b32_e32 v18, 1, v69
	v_or_b32_e32 v90, v96, v47
	v_lshl_add_u64 v[86:87], v[20:21], 0, v[18:19]
	v_lshlrev_b32_e32 v18, 11, v88
	v_or_b32_e32 v101, v96, v49
	v_lshl_add_u64 v[88:89], v[86:87], 0, v[18:19]
	v_lshlrev_b32_e32 v18, 11, v90
	v_lshl_add_u64 v[90:91], v[86:87], 0, v[18:19]
	v_lshlrev_b32_e32 v18, 11, v101
	s_waitcnt vmcnt(7)
	ds_write2_b32 v62, v2, v3 offset1:1
	ds_write2_b32 v62, v4, v5 offset0:2 offset1:3
	s_waitcnt vmcnt(6)
	ds_write2_b32 v63, v6, v7 offset1:1
	ds_write2_b32 v64, v8, v9 offset1:1
	s_waitcnt vmcnt(5)
	ds_write2_b32 v65, v10, v11 offset1:1
	ds_write2_b32 v66, v12, v13 offset1:1
	s_waitcnt vmcnt(4)
	ds_write2_b32 v67, v42, v43 offset1:1
	ds_write2_b32 v68, v44, v45 offset1:1
	s_waitcnt vmcnt(3)
	ds_write2_b32 v92, v70, v71 offset1:1
	ds_write2_b32 v93, v72, v73 offset1:1
	s_waitcnt vmcnt(2)
	ds_write2_b32 v94, v74, v75 offset1:1
	ds_write2_b32 v95, v76, v77 offset1:1
	s_waitcnt vmcnt(1)
	ds_write2_b32 v97, v78, v79 offset1:1
	ds_write2_b32 v98, v80, v81 offset1:1
	s_waitcnt vmcnt(0)
	ds_write2_b32 v99, v82, v83 offset1:1
	ds_write2_b32 v100, v84, v85 offset1:1
	s_waitcnt lgkmcnt(0)
	ds_read2_b32 v[6:7], v57 offset0:33 offset1:41
	ds_read2_b32 v[8:9], v57 offset1:8
	ds_read2_b32 v[10:11], v57 offset0:66 offset1:74
	ds_read2_b32 v[12:13], v57 offset0:99 offset1:107
	ds_read2_b32 v[42:43], v57 offset0:132 offset1:140
	ds_read2_b32 v[44:45], v57 offset0:165 offset1:173
	ds_read2_b32 v[70:71], v57 offset0:198 offset1:206
	ds_read2_b32 v[72:73], v57 offset0:231 offset1:239
	ds_read2_b32 v[74:75], v57 offset0:49 offset1:57
	ds_read2_b32 v[76:77], v57 offset0:16 offset1:24
	ds_read2_b32 v[78:79], v57 offset0:82 offset1:90
	ds_read2_b32 v[80:81], v57 offset0:115 offset1:123
	ds_read2_b32 v[82:83], v57 offset0:148 offset1:156
	ds_read2_b32 v[84:85], v57 offset0:181 offset1:189
	ds_read2_b32 v[92:93], v57 offset0:214 offset1:222
	ds_read2_b32 v[94:95], v57 offset0:247 offset1:255
	s_waitcnt lgkmcnt(14)
	v_cvt_pk_bf16_f32 v2, v8, v6
	s_waitcnt lgkmcnt(12)
	v_cvt_pk_bf16_f32 v3, v10, v12
	s_waitcnt lgkmcnt(10)
	v_cvt_pk_bf16_f32 v4, v42, v44
	s_waitcnt lgkmcnt(8)
	v_cvt_pk_bf16_f32 v5, v70, v72
	v_cvt_pk_bf16_f32 v6, v9, v7
	v_cvt_pk_bf16_f32 v7, v11, v13
	v_cvt_pk_bf16_f32 v8, v43, v45
	v_cvt_pk_bf16_f32 v9, v71, v73
	global_store_dwordx4 v[88:89], v[2:5], off sc1
	global_store_dwordx4 v[90:91], v[6:9], off sc1
	s_waitcnt lgkmcnt(6)
	v_cvt_pk_bf16_f32 v10, v76, v74
	s_waitcnt lgkmcnt(4)
	v_cvt_pk_bf16_f32 v11, v78, v80
	v_or_b32_e32 v6, v96, v51
	s_waitcnt lgkmcnt(2)
	v_cvt_pk_bf16_f32 v12, v82, v84
	s_waitcnt lgkmcnt(0)
	v_cvt_pk_bf16_f32 v13, v92, v94
	v_lshl_add_u64 v[2:3], v[86:87], 0, v[18:19]
	v_lshlrev_b32_e32 v18, 11, v6
	global_store_dwordx4 v[2:3], v[10:13], off sc1
	v_cvt_pk_bf16_f32 v2, v77, v75
	v_cvt_pk_bf16_f32 v3, v79, v81
	v_cvt_pk_bf16_f32 v4, v83, v85
	v_cvt_pk_bf16_f32 v5, v93, v95
	v_lshl_add_u64 v[6:7], v[86:87], 0, v[18:19]
	global_store_dwordx4 v[6:7], v[2:5], off sc1
	s_waitcnt lgkmcnt(0)

.LBB0_197:
	s_waitcnt vmcnt(0)
	v_pk_mul_f32 v[2:3], v[6:7], v[12:13] op_sel_hi:[1,0]
	v_add_u32_e32 v4, 0x14a0, v44
	ds_write2_b32 v4, v2, v3 offset1:1
	v_pk_mul_f32 v[2:3], v[8:9], v[12:13] op_sel_hi:[1,0]
	v_add_u32_e32 v4, 0x14a8, v44
	ds_write2_b32 v4, v2, v3 offset1:1
	v_and_b32_e32 v2, 4, v42
	v_cmp_eq_u32_e32 vcc, 0, v2
	s_and_b64 vcc, s[8:9], vcc
	s_waitcnt lgkmcnt(0)
	v_lshlrev_b32_e32 v69, 5, v42
	v_cndmask_b32_e32 v2, v14, v58, vcc
	v_lshl_add_u32 v8, v2, 2, v56
	ds_read2_b32 v[2:3], v8 offset1:33
	ds_read2_b32 v[4:5], v8 offset0:66 offset1:99
	ds_read2_b32 v[6:7], v8 offset0:132 offset1:165
	ds_read2_b32 v[8:9], v8 offset0:198 offset1:231
	v_lshlrev_b32_e32 v18, 1, v13
	s_waitcnt lgkmcnt(3)
	v_cvt_pk_bf16_f32 v2, v2, v3
	s_waitcnt lgkmcnt(2)
	v_cvt_pk_bf16_f32 v3, v4, v5
	s_waitcnt lgkmcnt(1)
	v_cvt_pk_bf16_f32 v4, v6, v7
	v_or_b32_e32 v6, v69, v14
	v_lshl_add_u64 v[10:11], v[22:23], 0, v[18:19]
	s_waitcnt lgkmcnt(0)
	v_cvt_pk_bf16_f32 v5, v8, v9
	v_lshlrev_b32_e32 v18, 11, v6
	v_cndmask_b32_e32 v8, v47, v59, vcc
	v_lshl_add_u64 v[6:7], v[10:11], 0, v[18:19]
	v_lshl_add_u32 v18, v8, 2, v56
	ds_read2_b32 v[8:9], v18 offset1:33
	ds_read2_b32 v[12:13], v18 offset0:66 offset1:99
	ds_read2_b32 v[42:43], v18 offset0:132 offset1:165
	ds_read2_b32 v[44:45], v18 offset0:198 offset1:231
	global_store_dwordx4 v[6:7], v[2:5], off sc1
	v_or_b32_e32 v6, v69, v47
	v_lshlrev_b32_e32 v18, 11, v6
	s_waitcnt lgkmcnt(3)
	v_cvt_pk_bf16_f32 v2, v8, v9
	s_waitcnt lgkmcnt(2)
	v_cvt_pk_bf16_f32 v3, v12, v13
	s_waitcnt lgkmcnt(1)
	v_cvt_pk_bf16_f32 v4, v42, v43
	s_waitcnt lgkmcnt(0)
	v_cvt_pk_bf16_f32 v5, v44, v45
	ds_read2_b32 v[8:9], v57 offset0:49 offset1:57
	ds_read2_b32 v[12:13], v57 offset0:16 offset1:24
	ds_read2_b32 v[42:43], v57 offset0:82 offset1:90
	ds_read2_b32 v[44:45], v57 offset0:115 offset1:123
	ds_read2_b32 v[70:71], v57 offset0:148 offset1:156
	ds_read2_b32 v[72:73], v57 offset0:181 offset1:189
	ds_read2_b32 v[74:75], v57 offset0:214 offset1:222
	ds_read2_b32 v[76:77], v57 offset0:247 offset1:255
	v_lshl_add_u64 v[6:7], v[10:11], 0, v[18:19]
	global_store_dwordx4 v[6:7], v[2:5], off sc1
	v_or_b32_e32 v6, v69, v49
	v_lshlrev_b32_e32 v18, 11, v6
	s_waitcnt lgkmcnt(6)
	v_cvt_pk_bf16_f32 v2, v12, v8
	s_waitcnt lgkmcnt(4)
	v_cvt_pk_bf16_f32 v3, v42, v44
	s_waitcnt lgkmcnt(2)
	v_cvt_pk_bf16_f32 v4, v70, v72
	s_waitcnt lgkmcnt(0)
	v_cvt_pk_bf16_f32 v5, v74, v76
	v_lshl_add_u64 v[6:7], v[10:11], 0, v[18:19]
	global_store_dwordx4 v[6:7], v[2:5], off sc1
	v_or_b32_e32 v6, v69, v51
	v_lshlrev_b32_e32 v18, 11, v6
	v_cvt_pk_bf16_f32 v2, v13, v9
	v_cvt_pk_bf16_f32 v3, v43, v45
	v_cvt_pk_bf16_f32 v4, v71, v73
	v_cvt_pk_bf16_f32 v5, v75, v77
	v_lshl_add_u64 v[6:7], v[10:11], 0, v[18:19]
	global_store_dwordx4 v[6:7], v[2:5], off sc1
	s_waitcnt lgkmcnt(0)

.LBB0_199:
	s_andn2_saveexec_b64 s[8:9], s[66:67]
	s_cbranch_execz .LBB0_201
	v_add_u32_e32 v69, 0x1500, v61
	v_and_b32_e32 v84, 0x1ffc0, v69
	v_and_b32_e32 v92, 0x3e0, v60
	v_lshlrev_b32_e32 v18, 2, v92
	v_or_b32_e32 v2, v84, v14
	v_lshl_add_u64 v[82:83], v[32:33], 0, v[18:19]
	v_lshlrev_b32_e32 v18, 12, v2
	v_or_b32_e32 v4, v84, v47
	v_lshl_add_u64 v[2:3], v[82:83], 0, v[18:19]
	v_lshlrev_b32_e32 v18, 12, v4
	v_or_b32_e32 v10, v84, v49
	v_lshl_add_u64 v[6:7], v[82:83], 0, v[18:19]
	v_lshlrev_b32_e32 v18, 12, v10
	v_or_b32_e32 v12, v84, v51
	v_lshl_add_u64 v[10:11], v[82:83], 0, v[18:19]
	v_lshlrev_b32_e32 v18, 12, v12
	v_lshl_add_u64 v[42:43], v[82:83], 0, v[18:19]
	v_or_b32_e32 v18, v84, v52
	v_lshlrev_b32_e32 v18, 12, v18
	v_lshl_add_u64 v[70:71], v[82:83], 0, v[18:19]
	v_or_b32_e32 v18, v84, v53
	v_lshlrev_b32_e32 v18, 12, v18
	v_lshl_add_u64 v[74:75], v[82:83], 0, v[18:19]
	global_load_dwordx4 v[2:5], v[2:3], off nt
	s_nop 0
	global_load_dwordx4 v[6:9], v[6:7], off nt
	s_nop 0
	global_load_dwordx4 v[10:13], v[10:11], off nt
	s_nop 0
	global_load_dwordx4 v[42:45], v[42:43], off nt
	s_nop 0
	global_load_dwordx4 v[70:73], v[70:71], off nt
	s_nop 0
	global_load_dwordx4 v[74:77], v[74:75], off nt
	v_or_b32_e32 v18, v84, v54
	v_lshlrev_b32_e32 v18, 12, v18
	v_lshl_add_u64 v[78:79], v[82:83], 0, v[18:19]
	v_or_b32_e32 v18, v84, v55
	global_load_dwordx4 v[78:81], v[78:79], off nt
	v_lshlrev_b32_e32 v18, 12, v18
	v_lshl_add_u64 v[82:83], v[82:83], 0, v[18:19]
	global_load_dwordx4 v[82:85], v[82:83], off nt
	v_add_u32_e32 v18, 0xfffe4c00, v61
	v_and_b32_e32 v18, 64, v18
	v_and_b32_e32 v69, 0x1ff80, v69
	v_or_b32_e32 v87, v92, v14
	v_sub_u32_e32 v86, v18, v69
	v_mul_u32_u24_e32 v69, 0xb00, v87
	v_ashrrev_i32_e32 v87, 31, v86
	v_lshl_add_u64 v[86:87], v[86:87], 1, s[42:43]
	v_lshlrev_b32_e32 v18, 1, v16
	v_add_u32_e32 v93, 0x1080, v62
	v_add_u32_e32 v94, 0x1088, v62
	v_add_u32_e32 v95, 0x14a0, v62
	v_add_u32_e32 v96, 0x14a8, v62
	v_add_u32_e32 v97, 0x18c0, v62
	v_add_u32_e32 v98, 0x18c8, v62
	v_add_u32_e32 v99, 0x1ce0, v62
	v_add_u32_e32 v100, 0x1ce8, v62
	v_lshl_add_u64 v[86:87], v[86:87], 0, v[18:19]
	v_or_b32_e32 v88, v92, v47
	v_lshlrev_b32_e32 v18, 1, v69
	v_lshl_add_u64 v[86:87], v[86:87], 0, s[24:25]
	v_mul_u32_u24_e32 v90, 0xb00, v88
	v_lshl_add_u64 v[88:89], v[86:87], 0, v[18:19]
	v_lshlrev_b32_e32 v18, 1, v90
	v_lshl_add_u64 v[90:91], v[86:87], 0, v[18:19]
	s_waitcnt vmcnt(7)
	ds_write2_b32 v62, v2, v3 offset1:1
	ds_write2_b32 v62, v4, v5 offset0:2 offset1:3
	s_waitcnt vmcnt(6)
	ds_write2_b32 v63, v6, v7 offset1:1
	ds_write2_b32 v64, v8, v9 offset1:1
	s_waitcnt vmcnt(5)
	ds_write2_b32 v65, v10, v11 offset1:1
	ds_write2_b32 v66, v12, v13 offset1:1
	s_waitcnt vmcnt(4)
	ds_write2_b32 v67, v42, v43 offset1:1
	ds_write2_b32 v68, v44, v45 offset1:1
	s_waitcnt vmcnt(3)
	ds_write2_b32 v93, v70, v71 offset1:1
	ds_write2_b32 v94, v72, v73 offset1:1
	s_waitcnt vmcnt(2)
	ds_write2_b32 v95, v74, v75 offset1:1
	ds_write2_b32 v96, v76, v77 offset1:1
	s_waitcnt vmcnt(1)
	ds_write2_b32 v97, v78, v79 offset1:1
	ds_write2_b32 v98, v80, v81 offset1:1
	s_waitcnt vmcnt(0)
	ds_write2_b32 v99, v82, v83 offset1:1
	ds_write2_b32 v100, v84, v85 offset1:1
	s_waitcnt lgkmcnt(0)
	ds_read2_b32 v[6:7], v57 offset0:33 offset1:41
	ds_read2_b32 v[8:9], v57 offset1:8
	ds_read2_b32 v[10:11], v57 offset0:66 offset1:74
	ds_read2_b32 v[12:13], v57 offset0:99 offset1:107
	ds_read2_b32 v[42:43], v57 offset0:132 offset1:140
	ds_read2_b32 v[44:45], v57 offset0:165 offset1:173
	ds_read2_b32 v[70:71], v57 offset0:198 offset1:206
	ds_read2_b32 v[72:73], v57 offset0:231 offset1:239
	ds_read2_b32 v[74:75], v57 offset0:16 offset1:24
	ds_read2_b32 v[76:77], v57 offset0:49 offset1:57
	ds_read2_b32 v[78:79], v57 offset0:82 offset1:90
	ds_read2_b32 v[80:81], v57 offset0:115 offset1:123
	ds_read2_b32 v[82:83], v57 offset0:148 offset1:156
	s_waitcnt lgkmcnt(11)
	v_cvt_pk_bf16_f32 v2, v8, v6
	s_waitcnt lgkmcnt(9)
	v_cvt_pk_bf16_f32 v3, v10, v12
	s_waitcnt lgkmcnt(7)
	v_cvt_pk_bf16_f32 v4, v42, v44
	s_waitcnt lgkmcnt(5)
	v_cvt_pk_bf16_f32 v5, v70, v72
	global_store_dwordx4 v[88:89], v[2:5], off sc1
	v_cvt_pk_bf16_f32 v6, v9, v7
	v_cvt_pk_bf16_f32 v7, v11, v13
	v_cvt_pk_bf16_f32 v8, v43, v45
	ds_read2_b32 v[10:11], v57 offset0:181 offset1:189
	ds_read2_b32 v[12:13], v57 offset0:214 offset1:222
	ds_read2_b32 v[42:43], v57 offset0:247 offset1:255
	v_cvt_pk_bf16_f32 v9, v71, v73
	global_store_dwordx4 v[90:91], v[6:9], off sc1
	s_waitcnt lgkmcnt(6)
	v_cvt_pk_bf16_f32 v2, v74, v76
	s_waitcnt lgkmcnt(4)
	v_cvt_pk_bf16_f32 v3, v78, v80
	v_or_b32_e32 v6, v92, v49
	v_mul_u32_u24_e32 v6, 0xb00, v6
	v_lshlrev_b32_e32 v18, 1, v6
	s_waitcnt lgkmcnt(2)
	v_cvt_pk_bf16_f32 v4, v82, v10
	s_waitcnt lgkmcnt(0)
	v_cvt_pk_bf16_f32 v5, v12, v42
	v_lshl_add_u64 v[6:7], v[86:87], 0, v[18:19]
	global_store_dwordx4 v[6:7], v[2:5], off sc1
	v_or_b32_e32 v6, v92, v51
	v_mul_u32_u24_e32 v6, 0xb00, v6
	v_lshlrev_b32_e32 v18, 1, v6
	v_cvt_pk_bf16_f32 v2, v75, v77
	v_cvt_pk_bf16_f32 v3, v79, v81
	v_cvt_pk_bf16_f32 v4, v83, v11
	v_cvt_pk_bf16_f32 v5, v13, v43
	v_lshl_add_u64 v[6:7], v[86:87], 0, v[18:19]
	global_store_dwordx4 v[6:7], v[2:5], off sc1
	s_waitcnt lgkmcnt(0)

.LBB0_202:
	s_andn2_saveexec_b64 s[8:9], s[64:65]
	s_cbranch_execz .LBB0_204
	v_add_u32_e32 v69, 0x2000, v61
	v_and_b32_e32 v84, 0x1ffc0, v69
	v_and_b32_e32 v92, 0x3e0, v60
	v_lshlrev_b32_e32 v18, 2, v92
	v_or_b32_e32 v2, v84, v14
	v_lshl_add_u64 v[82:83], v[34:35], 0, v[18:19]
	v_lshlrev_b32_e32 v18, 12, v2
	v_or_b32_e32 v4, v84, v47
	v_lshl_add_u64 v[2:3], v[82:83], 0, v[18:19]
	v_lshlrev_b32_e32 v18, 12, v4
	v_or_b32_e32 v10, v84, v49
	v_lshl_add_u64 v[6:7], v[82:83], 0, v[18:19]
	v_lshlrev_b32_e32 v18, 12, v10
	v_or_b32_e32 v12, v84, v51
	v_lshl_add_u64 v[10:11], v[82:83], 0, v[18:19]
	v_lshlrev_b32_e32 v18, 12, v12
	v_lshl_add_u64 v[42:43], v[82:83], 0, v[18:19]
	v_or_b32_e32 v18, v84, v52
	v_lshlrev_b32_e32 v18, 12, v18
	v_lshl_add_u64 v[70:71], v[82:83], 0, v[18:19]
	v_or_b32_e32 v18, v84, v53
	v_lshlrev_b32_e32 v18, 12, v18
	v_lshl_add_u64 v[74:75], v[82:83], 0, v[18:19]
	global_load_dwordx4 v[2:5], v[2:3], off nt
	s_nop 0
	global_load_dwordx4 v[6:9], v[6:7], off nt
	s_nop 0
	global_load_dwordx4 v[10:13], v[10:11], off nt
	s_nop 0
	global_load_dwordx4 v[42:45], v[42:43], off nt
	s_nop 0
	global_load_dwordx4 v[70:73], v[70:71], off nt
	s_nop 0
	global_load_dwordx4 v[74:77], v[74:75], off nt
	v_or_b32_e32 v18, v84, v54
	v_lshlrev_b32_e32 v18, 12, v18
	v_lshl_add_u64 v[78:79], v[82:83], 0, v[18:19]
	v_or_b32_e32 v18, v84, v55
	global_load_dwordx4 v[78:81], v[78:79], off nt
	v_lshlrev_b32_e32 v18, 12, v18
	v_lshl_add_u64 v[82:83], v[82:83], 0, v[18:19]
	global_load_dwordx4 v[82:85], v[82:83], off nt
	v_add_u32_e32 v18, 0xfffe4c00, v61
	v_and_b32_e32 v18, 64, v18
	v_and_b32_e32 v69, 0x1ff80, v69
	v_or_b32_e32 v87, v92, v14
	v_sub_u32_e32 v86, v18, v69
	v_mul_u32_u24_e32 v69, 0xb00, v87
	v_ashrrev_i32_e32 v87, 31, v86
	v_lshl_add_u64 v[86:87], v[86:87], 1, s[42:43]
	v_lshlrev_b32_e32 v18, 1, v16
	v_add_u32_e32 v93, 0x1080, v62
	v_add_u32_e32 v94, 0x1088, v62
	v_add_u32_e32 v95, 0x14a0, v62
	v_add_u32_e32 v96, 0x14a8, v62
	v_add_u32_e32 v97, 0x18c0, v62
	v_add_u32_e32 v98, 0x18c8, v62
	v_add_u32_e32 v99, 0x1ce0, v62
	v_add_u32_e32 v100, 0x1ce8, v62
	v_lshl_add_u64 v[86:87], v[86:87], 0, v[18:19]
	v_or_b32_e32 v88, v92, v47
	v_lshlrev_b32_e32 v18, 1, v69
	v_lshl_add_u64 v[86:87], v[86:87], 0, s[50:51]
	v_mul_u32_u24_e32 v90, 0xb00, v88
	v_lshl_add_u64 v[88:89], v[86:87], 0, v[18:19]
	v_lshlrev_b32_e32 v18, 1, v90
	v_lshl_add_u64 v[90:91], v[86:87], 0, v[18:19]
	s_waitcnt vmcnt(7)
	ds_write2_b32 v62, v2, v3 offset1:1
	ds_write2_b32 v62, v4, v5 offset0:2 offset1:3
	s_waitcnt vmcnt(6)
	ds_write2_b32 v63, v6, v7 offset1:1
	ds_write2_b32 v64, v8, v9 offset1:1
	s_waitcnt vmcnt(5)
	ds_write2_b32 v65, v10, v11 offset1:1
	ds_write2_b32 v66, v12, v13 offset1:1
	s_waitcnt vmcnt(4)
	ds_write2_b32 v67, v42, v43 offset1:1
	ds_write2_b32 v68, v44, v45 offset1:1
	s_waitcnt vmcnt(3)
	ds_write2_b32 v93, v70, v71 offset1:1
	ds_write2_b32 v94, v72, v73 offset1:1
	s_waitcnt vmcnt(2)
	ds_write2_b32 v95, v74, v75 offset1:1
	ds_write2_b32 v96, v76, v77 offset1:1
	s_waitcnt vmcnt(1)
	ds_write2_b32 v97, v78, v79 offset1:1
	ds_write2_b32 v98, v80, v81 offset1:1
	s_waitcnt vmcnt(0)
	ds_write2_b32 v99, v82, v83 offset1:1
	ds_write2_b32 v100, v84, v85 offset1:1
	s_waitcnt lgkmcnt(0)
	ds_read2_b32 v[6:7], v57 offset0:33 offset1:41
	ds_read2_b32 v[8:9], v57 offset1:8
	ds_read2_b32 v[10:11], v57 offset0:66 offset1:74
	ds_read2_b32 v[12:13], v57 offset0:99 offset1:107
	ds_read2_b32 v[42:43], v57 offset0:132 offset1:140
	ds_read2_b32 v[44:45], v57 offset0:165 offset1:173
	ds_read2_b32 v[70:71], v57 offset0:198 offset1:206
	ds_read2_b32 v[72:73], v57 offset0:231 offset1:239
	ds_read2_b32 v[74:75], v57 offset0:16 offset1:24
	ds_read2_b32 v[76:77], v57 offset0:49 offset1:57
	ds_read2_b32 v[78:79], v57 offset0:82 offset1:90
	ds_read2_b32 v[80:81], v57 offset0:115 offset1:123
	ds_read2_b32 v[82:83], v57 offset0:148 offset1:156
	s_waitcnt lgkmcnt(11)
	v_cvt_pk_bf16_f32 v2, v8, v6
	s_waitcnt lgkmcnt(9)
	v_cvt_pk_bf16_f32 v3, v10, v12
	s_waitcnt lgkmcnt(7)
	v_cvt_pk_bf16_f32 v4, v42, v44
	s_waitcnt lgkmcnt(5)
	v_cvt_pk_bf16_f32 v5, v70, v72
	global_store_dwordx4 v[88:89], v[2:5], off sc1
	v_cvt_pk_bf16_f32 v6, v9, v7
	v_cvt_pk_bf16_f32 v7, v11, v13
	v_cvt_pk_bf16_f32 v8, v43, v45
	ds_read2_b32 v[10:11], v57 offset0:181 offset1:189
	ds_read2_b32 v[12:13], v57 offset0:214 offset1:222
	ds_read2_b32 v[42:43], v57 offset0:247 offset1:255
	v_cvt_pk_bf16_f32 v9, v71, v73
	global_store_dwordx4 v[90:91], v[6:9], off sc1
	s_waitcnt lgkmcnt(6)
	v_cvt_pk_bf16_f32 v2, v74, v76
	s_waitcnt lgkmcnt(4)
	v_cvt_pk_bf16_f32 v3, v78, v80
	v_or_b32_e32 v6, v92, v49
	v_mul_u32_u24_e32 v6, 0xb00, v6
	v_lshlrev_b32_e32 v18, 1, v6
	s_waitcnt lgkmcnt(2)
	v_cvt_pk_bf16_f32 v4, v82, v10
	s_waitcnt lgkmcnt(0)
	v_cvt_pk_bf16_f32 v5, v12, v42
	v_lshl_add_u64 v[6:7], v[86:87], 0, v[18:19]
	global_store_dwordx4 v[6:7], v[2:5], off sc1
	v_or_b32_e32 v6, v92, v51
	v_mul_u32_u24_e32 v6, 0xb00, v6
	v_lshlrev_b32_e32 v18, 1, v6
	v_cvt_pk_bf16_f32 v2, v75, v77
	v_cvt_pk_bf16_f32 v3, v79, v81
	v_cvt_pk_bf16_f32 v4, v83, v11
	v_cvt_pk_bf16_f32 v5, v13, v43
	v_lshl_add_u64 v[6:7], v[86:87], 0, v[18:19]
	global_store_dwordx4 v[6:7], v[2:5], off sc1
	s_waitcnt lgkmcnt(0)

.LBB0_222:
	s_waitcnt vmcnt(0)
	v_pk_mul_f32 v[2:3], v[6:7], v[12:13] op_sel_hi:[1,0]
	v_add_u32_e32 v4, 0x14a0, v44
	ds_write2_b32 v4, v2, v3 offset1:1
	v_pk_mul_f32 v[2:3], v[8:9], v[12:13] op_sel_hi:[1,0]
	v_add_u32_e32 v4, 0x14a8, v44
	ds_write2_b32 v4, v2, v3 offset1:1
	s_waitcnt lgkmcnt(0)
	v_lshlrev_b32_e32 v69, 5, v42
	v_lshlrev_b32_e32 v18, 1, v13
	ds_read2_b32 v[6:7], v57 offset0:33 offset1:41
	ds_read2_b32 v[8:9], v57 offset1:8
	ds_read2_b32 v[10:11], v57 offset0:66 offset1:74
	ds_read2_b32 v[12:13], v57 offset0:99 offset1:107
	ds_read2_b32 v[42:43], v57 offset0:132 offset1:140
	ds_read2_b32 v[44:45], v57 offset0:165 offset1:173
	ds_read2_b32 v[70:71], v57 offset0:198 offset1:206
	ds_read2_b32 v[72:73], v57 offset0:231 offset1:239
	s_waitcnt lgkmcnt(6)
	v_cvt_pk_bf16_f32 v2, v8, v6
	v_or_b32_e32 v6, v69, v14
	v_lshl_add_u64 v[74:75], v[24:25], 0, v[18:19]
	v_lshlrev_b32_e32 v18, 11, v6
	s_waitcnt lgkmcnt(4)
	v_cvt_pk_bf16_f32 v3, v10, v12
	s_waitcnt lgkmcnt(2)
	v_cvt_pk_bf16_f32 v4, v42, v44
	s_waitcnt lgkmcnt(0)
	v_cvt_pk_bf16_f32 v5, v70, v72
	v_lshl_add_u64 v[76:77], v[74:75], 0, v[18:19]
	global_store_dwordx4 v[76:77], v[2:5], off sc1
	v_or_b32_e32 v6, v69, v47
	v_lshlrev_b32_e32 v18, 11, v6
	v_cvt_pk_bf16_f32 v2, v9, v7
	v_cvt_pk_bf16_f32 v3, v11, v13
	v_cvt_pk_bf16_f32 v4, v43, v45
	v_cvt_pk_bf16_f32 v5, v71, v73
	ds_read2_b32 v[8:9], v57 offset0:49 offset1:57
	ds_read2_b32 v[10:11], v57 offset0:16 offset1:24
	ds_read2_b32 v[12:13], v57 offset0:82 offset1:90
	ds_read2_b32 v[42:43], v57 offset0:115 offset1:123
	ds_read2_b32 v[44:45], v57 offset0:148 offset1:156
	ds_read2_b32 v[70:71], v57 offset0:181 offset1:189
	ds_read2_b32 v[72:73], v57 offset0:214 offset1:222
	ds_read2_b32 v[76:77], v57 offset0:247 offset1:255
	v_lshl_add_u64 v[6:7], v[74:75], 0, v[18:19]
	global_store_dwordx4 v[6:7], v[2:5], off sc1
	v_or_b32_e32 v6, v69, v49
	v_lshlrev_b32_e32 v18, 11, v6
	s_waitcnt lgkmcnt(6)
	v_cvt_pk_bf16_f32 v2, v10, v8
	s_waitcnt lgkmcnt(4)
	v_cvt_pk_bf16_f32 v3, v12, v42
	s_waitcnt lgkmcnt(2)
	v_cvt_pk_bf16_f32 v4, v44, v70
	s_waitcnt lgkmcnt(0)
	v_cvt_pk_bf16_f32 v5, v72, v76
	v_lshl_add_u64 v[6:7], v[74:75], 0, v[18:19]
	global_store_dwordx4 v[6:7], v[2:5], off sc1
	v_or_b32_e32 v6, v69, v51
	v_lshlrev_b32_e32 v18, 11, v6
	v_cvt_pk_bf16_f32 v2, v11, v9
	v_cvt_pk_bf16_f32 v3, v13, v43
	v_cvt_pk_bf16_f32 v4, v45, v71
	v_cvt_pk_bf16_f32 v5, v73, v77
	v_lshl_add_u64 v[6:7], v[74:75], 0, v[18:19]
	global_store_dwordx4 v[6:7], v[2:5], off sc1
	s_waitcnt lgkmcnt(0)

.LBB0_270:
	v_add_u32_e32 v2, s3, v10
	v_cmp_gt_i32_e64 s[10:11], s13, v2
	s_nop 1
	v_cndmask_b32_e64 v20, v17, v19, s[10:11]
	v_perm_b32 v20, v20, v2, s14
	v_lshlrev_b32_e32 v2, 12, v20
	v_lshl_add_u64 v[38:39], v[4:5], 0, v[2:3]
	s_waitcnt lgkmcnt(0)
	global_load_dwordx4 v[22:25], v[38:39], off nt
	global_load_dwordx4 v[26:29], v[38:39], off offset:1024 nt
	global_load_dwordx4 v[30:33], v[38:39], off offset:2048 nt
	global_load_dwordx4 v[34:37], v[38:39], off offset:3072 nt
	s_waitcnt vmcnt(3)
	v_mul_f32_e32 v2, v23, v23
	v_mul_f32_e32 v21, v25, v25
	s_waitcnt vmcnt(2)
	v_mul_f32_e32 v38, v27, v27
	v_mul_f32_e32 v39, v29, v29
	s_waitcnt vmcnt(1)
	v_mul_f32_e32 v40, v31, v31
	v_mul_f32_e32 v42, v33, v33
	v_fmac_f32_e32 v2, v22, v22
	v_fmac_f32_e32 v21, v24, v24
	v_fmac_f32_e32 v38, v26, v26
	v_fmac_f32_e32 v39, v28, v28
	s_waitcnt vmcnt(0)
	v_mul_f32_e32 v43, v35, v35
	v_mul_f32_e32 v44, v37, v37
	v_fmac_f32_e32 v40, v30, v30
	v_fmac_f32_e32 v42, v32, v32
	v_add_f32_e32 v2, v2, v21
	v_add_f32_e32 v21, v38, v39
	v_fmac_f32_e32 v43, v34, v34
	v_fmac_f32_e32 v44, v36, v36
	v_add_f32_e32 v38, v40, v42
	v_add_f32_e32 v2, v2, v21
	v_add_f32_e32 v39, v43, v44
	v_add_f32_e32 v2, v2, v38
	v_add_f32_e32 v2, v2, v39
	ds_bpermute_b32 v21, v11, v2
	v_cvt_pk_bf16_f32 v22, v22, v23
	v_cvt_pk_bf16_f32 v23, v24, v25
	v_cvt_pk_bf16_f32 v24, v26, v27
	v_cvt_pk_bf16_f32 v25, v28, v29
	s_waitcnt lgkmcnt(0)
	v_add_f32_e32 v2, v2, v21
	ds_bpermute_b32 v21, v12, v2
	v_cvt_pk_bf16_f32 v26, v30, v31
	v_cvt_pk_bf16_f32 v27, v32, v33
	s_waitcnt lgkmcnt(0)
	v_add_f32_e32 v21, v2, v21
	ds_bpermute_b32 v38, v13, v21
	v_lshlrev_b32_e32 v2, 11, v20
	s_waitcnt lgkmcnt(0)
	v_add_f32_e32 v21, v21, v38
	ds_bpermute_b32 v40, v15, v21
	v_lshl_add_u64 v[38:39], v[6:7], 0, v[2:3]
	global_store_dwordx2 v[38:39], v[22:23], off sc1
	global_store_dwordx2 v[38:39], v[24:25], off offset:512 sc1
	v_cvt_pk_bf16_f32 v24, v34, v35
	v_cvt_pk_bf16_f32 v25, v36, v37
	s_waitcnt lgkmcnt(0)
	v_add_f32_e32 v2, v21, v40
	ds_bpermute_b32 v21, v16, v2
	global_store_dwordx2 v[38:39], v[26:27], off offset:1024 sc1
	global_store_dwordx2 v[38:39], v[24:25], off offset:1536 sc1
	s_waitcnt lgkmcnt(0)
	v_add_f32_e32 v21, v2, v21
	ds_bpermute_b32 v22, v18, v21
	s_and_saveexec_b64 s[10:11], vcc
	s_cbranch_execz .LBB0_269
	v_lshlrev_b32_e32 v2, 6, v20
	v_lshl_add_u64 v[24:25], v[8:9], 0, v[2:3]
	s_waitcnt lgkmcnt(0)
	v_add_f32_e32 v2, v21, v22
	v_cndmask_b32_e64 v2, 0, v2, s[8:9]
	global_store_dword v[24:25], v2, off
	s_branch .LBB0_269

.LBB0_285:
	s_waitcnt vmcnt(0)
	v_pk_mul_f32 v[2:3], v[2:3], v[6:7] op_sel_hi:[1,0]
	v_add_u32_e32 v7, 0x14a0, v67
	ds_write2_b32 v7, v2, v3 offset1:1
	v_pk_mul_f32 v[2:3], v[4:5], v[6:7] op_sel_hi:[1,0]
	v_add_u32_e32 v4, 0x14a8, v67
	ds_write2_b32 v4, v2, v3 offset1:1
	s_waitcnt lgkmcnt(0)
	ds_read2_b32 v[6:7], v55 offset0:33 offset1:41
	ds_read2_b32 v[8:9], v55 offset1:8
	ds_read2_b32 v[10:11], v55 offset0:66 offset1:74
	ds_read2_b32 v[12:13], v55 offset0:99 offset1:107
	ds_read2_b32 v[44:45], v55 offset0:132 offset1:140
	ds_read2_b32 v[68:69], v55 offset0:165 offset1:173
	ds_read2_b32 v[70:71], v55 offset0:198 offset1:206
	ds_read2_b32 v[72:73], v55 offset0:231 offset1:239
	s_waitcnt lgkmcnt(6)
	v_cvt_pk_bf16_f32 v2, v8, v6
	v_mul_lo_u32 v6, v66, s71
	v_add3_u32 v66, v14, v58, v6
	v_ashrrev_i32_e32 v67, 31, v66
	v_lshl_add_u64 v[42:43], v[42:43], 1, v[28:29]
	v_lshlrev_b64 v[74:75], 11, v[66:67]
	s_waitcnt lgkmcnt(4)
	v_cvt_pk_bf16_f32 v3, v10, v12
	s_waitcnt lgkmcnt(2)
	v_cvt_pk_bf16_f32 v4, v44, v68
	s_waitcnt lgkmcnt(0)
	v_cvt_pk_bf16_f32 v5, v70, v72
	v_lshl_add_u64 v[74:75], v[42:43], 0, v[74:75]
	v_add_u32_e32 v6, 8, v66
	global_store_dwordx4 v[74:75], v[2:5], off sc1
	s_nop 1
	v_cvt_pk_bf16_f32 v2, v9, v7
	v_ashrrev_i32_e32 v7, 31, v6
	v_cvt_pk_bf16_f32 v3, v11, v13
	v_cvt_pk_bf16_f32 v4, v45, v69
	v_cvt_pk_bf16_f32 v5, v71, v73
	v_lshlrev_b64 v[6:7], 11, v[6:7]
	ds_read2_b32 v[8:9], v55 offset0:49 offset1:57
	ds_read2_b32 v[10:11], v55 offset0:16 offset1:24
	ds_read2_b32 v[12:13], v55 offset0:82 offset1:90
	ds_read2_b32 v[44:45], v55 offset0:115 offset1:123
	ds_read2_b32 v[68:69], v55 offset0:148 offset1:156
	ds_read2_b32 v[70:71], v55 offset0:181 offset1:189
	ds_read2_b32 v[72:73], v55 offset0:214 offset1:222
	ds_read2_b32 v[74:75], v55 offset0:247 offset1:255
	v_lshl_add_u64 v[6:7], v[42:43], 0, v[6:7]
	global_store_dwordx4 v[6:7], v[2:5], off sc1
	v_add_u32_e32 v6, 16, v66
	v_ashrrev_i32_e32 v7, 31, v6
	v_lshlrev_b64 v[6:7], 11, v[6:7]
	s_waitcnt lgkmcnt(6)
	v_cvt_pk_bf16_f32 v2, v10, v8
	s_waitcnt lgkmcnt(4)
	v_cvt_pk_bf16_f32 v3, v12, v44
	s_waitcnt lgkmcnt(2)
	v_cvt_pk_bf16_f32 v4, v68, v70
	s_waitcnt lgkmcnt(0)
	v_cvt_pk_bf16_f32 v5, v72, v74
	v_lshl_add_u64 v[6:7], v[42:43], 0, v[6:7]
	global_store_dwordx4 v[6:7], v[2:5], off sc1
	v_add_u32_e32 v6, 24, v66
	v_ashrrev_i32_e32 v7, 31, v6
	v_lshlrev_b64 v[6:7], 11, v[6:7]
	v_cvt_pk_bf16_f32 v2, v11, v9
	v_cvt_pk_bf16_f32 v3, v13, v45
	v_cvt_pk_bf16_f32 v4, v69, v71
	v_cvt_pk_bf16_f32 v5, v73, v75
	v_lshl_add_u64 v[6:7], v[42:43], 0, v[6:7]
	global_store_dwordx4 v[6:7], v[2:5], off sc1
	s_waitcnt lgkmcnt(0)

.LBB0_287:
	v_cmp_lt_i32_e32 vcc, s4, v16
	s_and_saveexec_b64 s[8:9], vcc
	s_xor_b64 s[50:51], exec, s[8:9]
	s_cbranch_execz .LBB0_337
	v_cmp_lt_u32_e32 vcc, s5, v16
	s_and_saveexec_b64 s[8:9], vcc
	s_xor_b64 s[52:53], exec, s[8:9]
	s_cbranch_execz .LBB0_318
	v_cmp_lt_u32_e32 vcc, s33, v16
	s_and_saveexec_b64 s[8:9], vcc
	s_xor_b64 s[54:55], exec, s[8:9]
	s_cbranch_execz .LBB0_315
	v_cmp_lt_u32_e32 vcc, s60, v16
	s_and_saveexec_b64 s[8:9], vcc
	s_xor_b64 s[64:65], exec, s[8:9]
	s_cbranch_execz .LBB0_312
	v_cmp_lt_u32_e32 vcc, s61, v16
	s_and_saveexec_b64 s[8:9], vcc
	s_xor_b64 s[8:9], exec, s[8:9]
	s_cbranch_execz .LBB0_293
	v_add_u32_e32 v2, 0x1b400, v59
	v_and_b32_e32 v82, 0x1ffc0, v2
	v_and_b32_e32 v92, 0x3e0, v58
	v_lshlrev_b32_e32 v20, 2, v92
	v_or_b32_e32 v2, v82, v14
	v_lshl_add_u64 v[78:79], v[30:31], 0, v[20:21]
	v_lshlrev_b32_e32 v20, 12, v2
	v_or_b32_e32 v4, v82, v17
	v_lshl_add_u64 v[2:3], v[78:79], 0, v[20:21]
	v_lshlrev_b32_e32 v20, 12, v4
	v_or_b32_e32 v10, v82, v47
	v_lshl_add_u64 v[6:7], v[78:79], 0, v[20:21]
	v_lshlrev_b32_e32 v20, 12, v10
	v_or_b32_e32 v12, v82, v49
	v_lshl_add_u64 v[10:11], v[78:79], 0, v[20:21]
	v_lshlrev_b32_e32 v20, 12, v12
	v_lshl_add_u64 v[42:43], v[78:79], 0, v[20:21]
	v_or_b32_e32 v20, v82, v50
	v_lshlrev_b32_e32 v20, 12, v20
	v_lshl_add_u64 v[66:67], v[78:79], 0, v[20:21]
	v_or_b32_e32 v20, v82, v51
	v_lshlrev_b32_e32 v20, 12, v20
	v_lshl_add_u64 v[70:71], v[78:79], 0, v[20:21]
	global_load_dwordx4 v[2:5], v[2:3], off nt
	s_nop 0
	global_load_dwordx4 v[6:9], v[6:7], off nt
	s_nop 0
	global_load_dwordx4 v[10:13], v[10:11], off nt
	s_nop 0
	global_load_dwordx4 v[42:45], v[42:43], off nt
	s_nop 0
	global_load_dwordx4 v[66:69], v[66:67], off nt
	s_nop 0
	global_load_dwordx4 v[70:73], v[70:71], off nt
	v_or_b32_e32 v20, v82, v52
	v_lshlrev_b32_e32 v20, 12, v20
	v_lshl_add_u64 v[74:75], v[78:79], 0, v[20:21]
	v_or_b32_e32 v20, v82, v53
	global_load_dwordx4 v[74:77], v[74:75], off nt
	v_lshlrev_b32_e32 v20, 12, v20
	v_lshl_add_u64 v[78:79], v[78:79], 0, v[20:21]
	global_load_dwordx4 v[78:81], v[78:79], off nt
	v_add_u32_e32 v88, 0xc68, v60
	v_add_u32_e32 v89, 0x1080, v60
	v_add_u32_e32 v90, 0x1088, v60
	v_add_u32_e32 v91, 0x14a0, v60
	v_add_u32_e32 v93, 0x14a8, v60
	v_add_u32_e32 v94, 0x18c0, v60
	v_add_u32_e32 v95, 0x18c8, v60
	v_add_u32_e32 v96, 0x1ce0, v60
	v_add_u32_e32 v97, 0x1ce8, v60
	v_or_b32_e32 v84, v92, v14
	v_lshlrev_b32_e32 v20, 1, v82
	v_or_b32_e32 v86, v92, v17
	v_lshl_add_u64 v[82:83], v[22:23], 0, v[20:21]
	v_lshlrev_b32_e32 v20, 11, v84
	v_lshl_add_u64 v[84:85], v[82:83], 0, v[20:21]
	v_lshlrev_b32_e32 v20, 11, v86
	v_lshl_add_u64 v[86:87], v[82:83], 0, v[20:21]
	s_waitcnt vmcnt(7)
	ds_write2_b32 v60, v2, v3 offset1:1
	ds_write2_b32 v60, v4, v5 offset0:2 offset1:3
	s_waitcnt vmcnt(6)
	ds_write2_b32 v61, v6, v7 offset1:1
	ds_write2_b32 v62, v8, v9 offset1:1
	s_waitcnt vmcnt(5)
	ds_write2_b32 v63, v10, v11 offset1:1
	ds_write2_b32 v64, v12, v13 offset1:1
	s_waitcnt vmcnt(4)
	ds_write2_b32 v65, v42, v43 offset1:1
	ds_write2_b32 v88, v44, v45 offset1:1
	s_waitcnt vmcnt(3)
	ds_write2_b32 v89, v66, v67 offset1:1
	ds_write2_b32 v90, v68, v69 offset1:1
	s_waitcnt vmcnt(2)
	ds_write2_b32 v91, v70, v71 offset1:1
	ds_write2_b32 v93, v72, v73 offset1:1
	s_waitcnt vmcnt(1)
	ds_write2_b32 v94, v74, v75 offset1:1
	ds_write2_b32 v95, v76, v77 offset1:1
	s_waitcnt vmcnt(0)
	ds_write2_b32 v96, v78, v79 offset1:1
	ds_write2_b32 v97, v80, v81 offset1:1
	s_waitcnt lgkmcnt(0)
	ds_read2_b32 v[6:7], v55 offset0:33 offset1:41
	ds_read2_b32 v[8:9], v55 offset1:8
	ds_read2_b32 v[10:11], v55 offset0:66 offset1:74
	ds_read2_b32 v[12:13], v55 offset0:99 offset1:107
	ds_read2_b32 v[42:43], v55 offset0:132 offset1:140
	ds_read2_b32 v[44:45], v55 offset0:165 offset1:173
	ds_read2_b32 v[66:67], v55 offset0:198 offset1:206
	ds_read2_b32 v[68:69], v55 offset0:231 offset1:239
	ds_read2_b32 v[70:71], v55 offset0:49 offset1:57
	ds_read2_b32 v[72:73], v55 offset0:16 offset1:24
	ds_read2_b32 v[74:75], v55 offset0:82 offset1:90
	ds_read2_b32 v[76:77], v55 offset0:115 offset1:123
	ds_read2_b32 v[78:79], v55 offset0:148 offset1:156
	ds_read2_b32 v[80:81], v55 offset0:181 offset1:189
	ds_read2_b32 v[88:89], v55 offset0:214 offset1:222
	ds_read2_b32 v[90:91], v55 offset0:247 offset1:255
	s_waitcnt lgkmcnt(14)
	v_cvt_pk_bf16_f32 v2, v8, v6
	s_waitcnt lgkmcnt(12)
	v_cvt_pk_bf16_f32 v3, v10, v12
	s_waitcnt lgkmcnt(10)
	v_cvt_pk_bf16_f32 v4, v42, v44
	s_waitcnt lgkmcnt(8)
	v_cvt_pk_bf16_f32 v5, v66, v68
	v_cvt_pk_bf16_f32 v6, v9, v7
	v_cvt_pk_bf16_f32 v7, v11, v13
	v_cvt_pk_bf16_f32 v8, v43, v45
	v_cvt_pk_bf16_f32 v9, v67, v69
	global_store_dwordx4 v[84:85], v[2:5], off sc1
	global_store_dwordx4 v[86:87], v[6:9], off sc1
	s_waitcnt lgkmcnt(6)
	v_cvt_pk_bf16_f32 v10, v72, v70
	v_or_b32_e32 v2, v92, v47
	v_lshlrev_b32_e32 v20, 11, v2
	v_or_b32_e32 v6, v92, v49
	s_waitcnt lgkmcnt(4)
	v_cvt_pk_bf16_f32 v11, v74, v76
	s_waitcnt lgkmcnt(2)
	v_cvt_pk_bf16_f32 v12, v78, v80
	s_waitcnt lgkmcnt(0)
	v_cvt_pk_bf16_f32 v13, v88, v90
	v_lshl_add_u64 v[2:3], v[82:83], 0, v[20:21]
	v_lshlrev_b32_e32 v20, 11, v6
	global_store_dwordx4 v[2:3], v[10:13], off sc1
	v_cvt_pk_bf16_f32 v2, v73, v71
	v_cvt_pk_bf16_f32 v3, v75, v77
	v_cvt_pk_bf16_f32 v4, v79, v81
	v_cvt_pk_bf16_f32 v5, v89, v91
	v_lshl_add_u64 v[6:7], v[82:83], 0, v[20:21]
	global_store_dwordx4 v[6:7], v[2:5], off sc1
	s_waitcnt lgkmcnt(0)

.LBB0_310:
	s_waitcnt vmcnt(0)
	v_pk_mul_f32 v[2:3], v[6:7], v[12:13] op_sel_hi:[1,0]
	v_add_u32_e32 v4, 0x14a0, v44
	ds_write2_b32 v4, v2, v3 offset1:1
	v_pk_mul_f32 v[2:3], v[8:9], v[12:13] op_sel_hi:[1,0]
	v_add_u32_e32 v4, 0x14a8, v44
	ds_write2_b32 v4, v2, v3 offset1:1
	v_and_b32_e32 v2, 4, v42
	v_cmp_eq_u32_e32 vcc, 0, v2
	s_and_b64 vcc, s[8:9], vcc
	s_waitcnt lgkmcnt(0)
	v_lshlrev_b32_e32 v74, 5, v42
	v_cndmask_b32_e32 v2, v14, v56, vcc
	v_lshl_add_u32 v8, v2, 2, v54
	ds_read2_b32 v[2:3], v8 offset1:33
	ds_read2_b32 v[4:5], v8 offset0:66 offset1:99
	ds_read2_b32 v[6:7], v8 offset0:132 offset1:165
	ds_read2_b32 v[8:9], v8 offset0:198 offset1:231
	v_lshlrev_b32_e32 v20, 1, v13
	s_waitcnt lgkmcnt(3)
	v_cvt_pk_bf16_f32 v2, v2, v3
	s_waitcnt lgkmcnt(2)
	v_cvt_pk_bf16_f32 v3, v4, v5
	s_waitcnt lgkmcnt(1)
	v_cvt_pk_bf16_f32 v4, v6, v7
	v_or_b32_e32 v6, v74, v14
	v_lshl_add_u64 v[10:11], v[24:25], 0, v[20:21]
	s_waitcnt lgkmcnt(0)
	v_cvt_pk_bf16_f32 v5, v8, v9
	v_lshlrev_b32_e32 v20, 11, v6
	v_cndmask_b32_e32 v8, v17, v57, vcc
	v_lshl_add_u64 v[6:7], v[10:11], 0, v[20:21]
	v_lshl_add_u32 v20, v8, 2, v54
	ds_read2_b32 v[8:9], v20 offset1:33
	ds_read2_b32 v[12:13], v20 offset0:66 offset1:99
	ds_read2_b32 v[42:43], v20 offset0:132 offset1:165
	ds_read2_b32 v[44:45], v20 offset0:198 offset1:231
	global_store_dwordx4 v[6:7], v[2:5], off sc1
	v_or_b32_e32 v6, v74, v17
	v_lshlrev_b32_e32 v20, 11, v6
	s_waitcnt lgkmcnt(3)
	v_cvt_pk_bf16_f32 v2, v8, v9
	s_waitcnt lgkmcnt(2)
	v_cvt_pk_bf16_f32 v3, v12, v13
	s_waitcnt lgkmcnt(1)
	v_cvt_pk_bf16_f32 v4, v42, v43
	s_waitcnt lgkmcnt(0)
	v_cvt_pk_bf16_f32 v5, v44, v45
	ds_read2_b32 v[8:9], v55 offset0:49 offset1:57
	ds_read2_b32 v[12:13], v55 offset0:16 offset1:24
	ds_read2_b32 v[42:43], v55 offset0:82 offset1:90
	ds_read2_b32 v[44:45], v55 offset0:115 offset1:123
	ds_read2_b32 v[66:67], v55 offset0:148 offset1:156
	ds_read2_b32 v[68:69], v55 offset0:181 offset1:189
	ds_read2_b32 v[70:71], v55 offset0:214 offset1:222
	ds_read2_b32 v[72:73], v55 offset0:247 offset1:255
	v_lshl_add_u64 v[6:7], v[10:11], 0, v[20:21]
	global_store_dwordx4 v[6:7], v[2:5], off sc1
	v_or_b32_e32 v6, v74, v47
	v_lshlrev_b32_e32 v20, 11, v6
	s_waitcnt lgkmcnt(6)
	v_cvt_pk_bf16_f32 v2, v12, v8
	s_waitcnt lgkmcnt(4)
	v_cvt_pk_bf16_f32 v3, v42, v44
	s_waitcnt lgkmcnt(2)
	v_cvt_pk_bf16_f32 v4, v66, v68
	s_waitcnt lgkmcnt(0)
	v_cvt_pk_bf16_f32 v5, v70, v72
	v_lshl_add_u64 v[6:7], v[10:11], 0, v[20:21]
	global_store_dwordx4 v[6:7], v[2:5], off sc1
	v_or_b32_e32 v6, v74, v49
	v_lshlrev_b32_e32 v20, 11, v6
	v_cvt_pk_bf16_f32 v2, v13, v9
	v_cvt_pk_bf16_f32 v3, v43, v45
	v_cvt_pk_bf16_f32 v4, v67, v69
	v_cvt_pk_bf16_f32 v5, v71, v73
	v_lshl_add_u64 v[6:7], v[10:11], 0, v[20:21]
	global_store_dwordx4 v[6:7], v[2:5], off sc1
	s_waitcnt lgkmcnt(0)

.LBB0_312:
	s_andn2_saveexec_b64 s[8:9], s[64:65]
	s_cbranch_execz .LBB0_314
	v_add_u32_e32 v82, 0x1c900, v59
	v_and_b32_e32 v80, 0x1ffc0, v82
	v_and_b32_e32 v88, 0x3e0, v58
	v_lshlrev_b32_e32 v20, 2, v88
	v_or_b32_e32 v2, v80, v14
	v_lshl_add_u64 v[78:79], v[34:35], 0, v[20:21]
	v_lshlrev_b32_e32 v20, 12, v2
	v_or_b32_e32 v4, v80, v17
	v_lshl_add_u64 v[2:3], v[78:79], 0, v[20:21]
	v_lshlrev_b32_e32 v20, 12, v4
	v_or_b32_e32 v10, v80, v47
	v_lshl_add_u64 v[6:7], v[78:79], 0, v[20:21]
	v_lshlrev_b32_e32 v20, 12, v10
	v_or_b32_e32 v12, v80, v49
	v_lshl_add_u64 v[10:11], v[78:79], 0, v[20:21]
	v_lshlrev_b32_e32 v20, 12, v12
	v_lshl_add_u64 v[42:43], v[78:79], 0, v[20:21]
	v_or_b32_e32 v20, v80, v50
	v_lshlrev_b32_e32 v20, 12, v20
	v_lshl_add_u64 v[66:67], v[78:79], 0, v[20:21]
	v_or_b32_e32 v20, v80, v51
	v_lshlrev_b32_e32 v20, 12, v20
	v_lshl_add_u64 v[70:71], v[78:79], 0, v[20:21]
	global_load_dwordx4 v[2:5], v[2:3], off nt
	s_nop 0
	global_load_dwordx4 v[6:9], v[6:7], off nt
	s_nop 0
	global_load_dwordx4 v[10:13], v[10:11], off nt
	s_nop 0
	global_load_dwordx4 v[42:45], v[42:43], off nt
	s_nop 0
	global_load_dwordx4 v[66:69], v[66:67], off nt
	s_nop 0
	global_load_dwordx4 v[70:73], v[70:71], off nt
	v_or_b32_e32 v20, v80, v52
	v_lshlrev_b32_e32 v20, 12, v20
	v_lshl_add_u64 v[74:75], v[78:79], 0, v[20:21]
	v_or_b32_e32 v20, v80, v53
	global_load_dwordx4 v[74:77], v[74:75], off nt
	v_lshlrev_b32_e32 v20, 12, v20
	v_lshl_add_u64 v[78:79], v[78:79], 0, v[20:21]
	global_load_dwordx4 v[78:81], v[78:79], off nt
	v_and_b32_e32 v20, 64, v59
	v_and_b32_e32 v82, 0x1ff80, v82
	v_or_b32_e32 v83, v88, v14
	v_sub_u32_e32 v82, v20, v82
	v_mul_u32_u24_e32 v85, 0xb00, v83
	v_ashrrev_i32_e32 v83, 31, v82
	v_lshl_add_u64 v[82:83], v[82:83], 1, s[40:41]
	v_lshlrev_b32_e32 v20, 1, v18
	v_add_u32_e32 v89, 0xc68, v60
	v_add_u32_e32 v90, 0x1080, v60
	v_add_u32_e32 v91, 0x1088, v60
	v_add_u32_e32 v92, 0x14a0, v60
	v_add_u32_e32 v93, 0x14a8, v60
	v_add_u32_e32 v94, 0x18c0, v60
	v_add_u32_e32 v95, 0x18c8, v60
	v_add_u32_e32 v96, 0x1ce0, v60
	v_add_u32_e32 v97, 0x1ce8, v60
	v_lshl_add_u64 v[82:83], v[82:83], 0, v[20:21]
	v_or_b32_e32 v84, v88, v17
	v_lshlrev_b32_e32 v20, 1, v85
	v_lshl_add_u64 v[82:83], v[82:83], 0, s[22:23]
	v_mul_u32_u24_e32 v86, 0xb00, v84
	v_lshl_add_u64 v[84:85], v[82:83], 0, v[20:21]
	v_lshlrev_b32_e32 v20, 1, v86
	v_lshl_add_u64 v[86:87], v[82:83], 0, v[20:21]
	s_waitcnt vmcnt(7)
	ds_write2_b32 v60, v2, v3 offset1:1
	ds_write2_b32 v60, v4, v5 offset0:2 offset1:3
	s_waitcnt vmcnt(6)
	ds_write2_b32 v61, v6, v7 offset1:1
	ds_write2_b32 v62, v8, v9 offset1:1
	s_waitcnt vmcnt(5)
	ds_write2_b32 v63, v10, v11 offset1:1
	ds_write2_b32 v64, v12, v13 offset1:1
	s_waitcnt vmcnt(4)
	ds_write2_b32 v65, v42, v43 offset1:1
	ds_write2_b32 v89, v44, v45 offset1:1
	s_waitcnt vmcnt(3)
	ds_write2_b32 v90, v66, v67 offset1:1
	ds_write2_b32 v91, v68, v69 offset1:1
	s_waitcnt vmcnt(2)
	ds_write2_b32 v92, v70, v71 offset1:1
	ds_write2_b32 v93, v72, v73 offset1:1
	s_waitcnt vmcnt(1)
	ds_write2_b32 v94, v74, v75 offset1:1
	ds_write2_b32 v95, v76, v77 offset1:1
	s_waitcnt vmcnt(0)
	ds_write2_b32 v96, v78, v79 offset1:1
	ds_write2_b32 v97, v80, v81 offset1:1
	s_waitcnt lgkmcnt(0)
	ds_read2_b32 v[6:7], v55 offset0:33 offset1:41
	ds_read2_b32 v[8:9], v55 offset1:8
	ds_read2_b32 v[10:11], v55 offset0:66 offset1:74
	ds_read2_b32 v[12:13], v55 offset0:99 offset1:107
	ds_read2_b32 v[42:43], v55 offset0:132 offset1:140
	ds_read2_b32 v[44:45], v55 offset0:165 offset1:173
	ds_read2_b32 v[66:67], v55 offset0:198 offset1:206
	ds_read2_b32 v[68:69], v55 offset0:231 offset1:239
	ds_read2_b32 v[70:71], v55 offset0:16 offset1:24
	ds_read2_b32 v[72:73], v55 offset0:49 offset1:57
	ds_read2_b32 v[74:75], v55 offset0:82 offset1:90
	ds_read2_b32 v[76:77], v55 offset0:115 offset1:123
	ds_read2_b32 v[78:79], v55 offset0:148 offset1:156
	s_waitcnt lgkmcnt(11)
	v_cvt_pk_bf16_f32 v2, v8, v6
	s_waitcnt lgkmcnt(9)
	v_cvt_pk_bf16_f32 v3, v10, v12
	s_waitcnt lgkmcnt(7)
	v_cvt_pk_bf16_f32 v4, v42, v44
	s_waitcnt lgkmcnt(5)
	v_cvt_pk_bf16_f32 v5, v66, v68
	global_store_dwordx4 v[84:85], v[2:5], off sc1
	v_cvt_pk_bf16_f32 v6, v9, v7
	v_cvt_pk_bf16_f32 v7, v11, v13
	v_cvt_pk_bf16_f32 v8, v43, v45
	ds_read2_b32 v[10:11], v55 offset0:181 offset1:189
	ds_read2_b32 v[12:13], v55 offset0:214 offset1:222
	ds_read2_b32 v[42:43], v55 offset0:247 offset1:255
	v_cvt_pk_bf16_f32 v9, v67, v69
	global_store_dwordx4 v[86:87], v[6:9], off sc1
	s_waitcnt lgkmcnt(6)
	v_cvt_pk_bf16_f32 v2, v70, v72
	s_waitcnt lgkmcnt(4)
	v_cvt_pk_bf16_f32 v3, v74, v76
	v_or_b32_e32 v6, v88, v47
	v_mul_u32_u24_e32 v6, 0xb00, v6
	v_lshlrev_b32_e32 v20, 1, v6
	s_waitcnt lgkmcnt(2)
	v_cvt_pk_bf16_f32 v4, v78, v10
	s_waitcnt lgkmcnt(0)
	v_cvt_pk_bf16_f32 v5, v12, v42
	v_lshl_add_u64 v[6:7], v[82:83], 0, v[20:21]
	global_store_dwordx4 v[6:7], v[2:5], off sc1
	v_or_b32_e32 v6, v88, v49
	v_mul_u32_u24_e32 v6, 0xb00, v6
	v_lshlrev_b32_e32 v20, 1, v6
	v_cvt_pk_bf16_f32 v2, v71, v73
	v_cvt_pk_bf16_f32 v3, v75, v77
	v_cvt_pk_bf16_f32 v4, v79, v11
	v_cvt_pk_bf16_f32 v5, v13, v43
	v_lshl_add_u64 v[6:7], v[82:83], 0, v[20:21]
	global_store_dwordx4 v[6:7], v[2:5], off sc1
	s_waitcnt lgkmcnt(0)

.LBB0_315:
	s_andn2_saveexec_b64 s[8:9], s[54:55]
	s_cbranch_execz .LBB0_317
	v_add_u32_e32 v82, 0x1d400, v59
	v_and_b32_e32 v80, 0x1ffc0, v82
	v_and_b32_e32 v88, 0x3e0, v58
	v_lshlrev_b32_e32 v20, 2, v88
	v_or_b32_e32 v2, v80, v14
	v_lshl_add_u64 v[78:79], v[36:37], 0, v[20:21]
	v_lshlrev_b32_e32 v20, 12, v2
	v_or_b32_e32 v4, v80, v17
	v_lshl_add_u64 v[2:3], v[78:79], 0, v[20:21]
	v_lshlrev_b32_e32 v20, 12, v4
	v_or_b32_e32 v10, v80, v47
	v_lshl_add_u64 v[6:7], v[78:79], 0, v[20:21]
	v_lshlrev_b32_e32 v20, 12, v10
	v_or_b32_e32 v12, v80, v49
	v_lshl_add_u64 v[10:11], v[78:79], 0, v[20:21]
	v_lshlrev_b32_e32 v20, 12, v12
	v_lshl_add_u64 v[42:43], v[78:79], 0, v[20:21]
	v_or_b32_e32 v20, v80, v50
	v_lshlrev_b32_e32 v20, 12, v20
	v_lshl_add_u64 v[66:67], v[78:79], 0, v[20:21]
	v_or_b32_e32 v20, v80, v51
	v_lshlrev_b32_e32 v20, 12, v20
	v_lshl_add_u64 v[70:71], v[78:79], 0, v[20:21]
	global_load_dwordx4 v[2:5], v[2:3], off nt
	s_nop 0
	global_load_dwordx4 v[6:9], v[6:7], off nt
	s_nop 0
	global_load_dwordx4 v[10:13], v[10:11], off nt
	s_nop 0
	global_load_dwordx4 v[42:45], v[42:43], off nt
	s_nop 0
	global_load_dwordx4 v[66:69], v[66:67], off nt
	s_nop 0
	global_load_dwordx4 v[70:73], v[70:71], off nt
	v_or_b32_e32 v20, v80, v52
	v_lshlrev_b32_e32 v20, 12, v20
	v_lshl_add_u64 v[74:75], v[78:79], 0, v[20:21]
	v_or_b32_e32 v20, v80, v53
	global_load_dwordx4 v[74:77], v[74:75], off nt
	v_lshlrev_b32_e32 v20, 12, v20
	v_lshl_add_u64 v[78:79], v[78:79], 0, v[20:21]
	global_load_dwordx4 v[78:81], v[78:79], off nt
	v_and_b32_e32 v20, 64, v59
	v_and_b32_e32 v82, 0x1ff80, v82
	v_or_b32_e32 v83, v88, v14
	v_sub_u32_e32 v82, v20, v82
	v_mul_u32_u24_e32 v85, 0xb00, v83
	v_ashrrev_i32_e32 v83, 31, v82
	v_lshl_add_u64 v[82:83], v[82:83], 1, s[40:41]
	v_lshlrev_b32_e32 v20, 1, v18
	v_add_u32_e32 v89, 0xc68, v60
	v_add_u32_e32 v90, 0x1080, v60
	v_add_u32_e32 v91, 0x1088, v60
	v_add_u32_e32 v92, 0x14a0, v60
	v_add_u32_e32 v93, 0x14a8, v60
	v_add_u32_e32 v94, 0x18c0, v60
	v_add_u32_e32 v95, 0x18c8, v60
	v_add_u32_e32 v96, 0x1ce0, v60
	v_add_u32_e32 v97, 0x1ce8, v60
	v_lshl_add_u64 v[82:83], v[82:83], 0, v[20:21]
	v_or_b32_e32 v84, v88, v17
	v_lshlrev_b32_e32 v20, 1, v85
	v_lshl_add_u64 v[82:83], v[82:83], 0, s[24:25]
	v_mul_u32_u24_e32 v86, 0xb00, v84
	v_lshl_add_u64 v[84:85], v[82:83], 0, v[20:21]
	v_lshlrev_b32_e32 v20, 1, v86
	v_lshl_add_u64 v[86:87], v[82:83], 0, v[20:21]
	s_waitcnt vmcnt(7)
	ds_write2_b32 v60, v2, v3 offset1:1
	ds_write2_b32 v60, v4, v5 offset0:2 offset1:3
	s_waitcnt vmcnt(6)
	ds_write2_b32 v61, v6, v7 offset1:1
	ds_write2_b32 v62, v8, v9 offset1:1
	s_waitcnt vmcnt(5)
	ds_write2_b32 v63, v10, v11 offset1:1
	ds_write2_b32 v64, v12, v13 offset1:1
	s_waitcnt vmcnt(4)
	ds_write2_b32 v65, v42, v43 offset1:1
	ds_write2_b32 v89, v44, v45 offset1:1
	s_waitcnt vmcnt(3)
	ds_write2_b32 v90, v66, v67 offset1:1
	ds_write2_b32 v91, v68, v69 offset1:1
	s_waitcnt vmcnt(2)
	ds_write2_b32 v92, v70, v71 offset1:1
	ds_write2_b32 v93, v72, v73 offset1:1
	s_waitcnt vmcnt(1)
	ds_write2_b32 v94, v74, v75 offset1:1
	ds_write2_b32 v95, v76, v77 offset1:1
	s_waitcnt vmcnt(0)
	ds_write2_b32 v96, v78, v79 offset1:1
	ds_write2_b32 v97, v80, v81 offset1:1
	s_waitcnt lgkmcnt(0)
	ds_read2_b32 v[6:7], v55 offset0:33 offset1:41
	ds_read2_b32 v[8:9], v55 offset1:8
	ds_read2_b32 v[10:11], v55 offset0:66 offset1:74
	ds_read2_b32 v[12:13], v55 offset0:99 offset1:107
	ds_read2_b32 v[42:43], v55 offset0:132 offset1:140
	ds_read2_b32 v[44:45], v55 offset0:165 offset1:173
	ds_read2_b32 v[66:67], v55 offset0:198 offset1:206
	ds_read2_b32 v[68:69], v55 offset0:231 offset1:239
	ds_read2_b32 v[70:71], v55 offset0:16 offset1:24
	ds_read2_b32 v[72:73], v55 offset0:49 offset1:57
	ds_read2_b32 v[74:75], v55 offset0:82 offset1:90
	ds_read2_b32 v[76:77], v55 offset0:115 offset1:123
	ds_read2_b32 v[78:79], v55 offset0:148 offset1:156
	s_waitcnt lgkmcnt(11)
	v_cvt_pk_bf16_f32 v2, v8, v6
	s_waitcnt lgkmcnt(9)
	v_cvt_pk_bf16_f32 v3, v10, v12
	s_waitcnt lgkmcnt(7)
	v_cvt_pk_bf16_f32 v4, v42, v44
	s_waitcnt lgkmcnt(5)
	v_cvt_pk_bf16_f32 v5, v66, v68
	global_store_dwordx4 v[84:85], v[2:5], off sc1
	v_cvt_pk_bf16_f32 v6, v9, v7
	v_cvt_pk_bf16_f32 v7, v11, v13
	v_cvt_pk_bf16_f32 v8, v43, v45
	ds_read2_b32 v[10:11], v55 offset0:181 offset1:189
	ds_read2_b32 v[12:13], v55 offset0:214 offset1:222
	ds_read2_b32 v[42:43], v55 offset0:247 offset1:255
	v_cvt_pk_bf16_f32 v9, v67, v69
	global_store_dwordx4 v[86:87], v[6:9], off sc1
	s_waitcnt lgkmcnt(6)
	v_cvt_pk_bf16_f32 v2, v70, v72
	s_waitcnt lgkmcnt(4)
	v_cvt_pk_bf16_f32 v3, v74, v76
	v_or_b32_e32 v6, v88, v47
	v_mul_u32_u24_e32 v6, 0xb00, v6
	v_lshlrev_b32_e32 v20, 1, v6
	s_waitcnt lgkmcnt(2)
	v_cvt_pk_bf16_f32 v4, v78, v10
	s_waitcnt lgkmcnt(0)
	v_cvt_pk_bf16_f32 v5, v12, v42
	v_lshl_add_u64 v[6:7], v[82:83], 0, v[20:21]
	global_store_dwordx4 v[6:7], v[2:5], off sc1
	v_or_b32_e32 v6, v88, v49
	v_mul_u32_u24_e32 v6, 0xb00, v6
	v_lshlrev_b32_e32 v20, 1, v6
	v_cvt_pk_bf16_f32 v2, v71, v73
	v_cvt_pk_bf16_f32 v3, v75, v77
	v_cvt_pk_bf16_f32 v4, v79, v11
	v_cvt_pk_bf16_f32 v5, v13, v43
	v_lshl_add_u64 v[6:7], v[82:83], 0, v[20:21]
	global_store_dwordx4 v[6:7], v[2:5], off sc1
	s_waitcnt lgkmcnt(0)

.LBB0_335:
	s_waitcnt vmcnt(0)
	v_pk_mul_f32 v[2:3], v[6:7], v[12:13] op_sel_hi:[1,0]
	v_add_u32_e32 v4, 0x14a0, v44
	ds_write2_b32 v4, v2, v3 offset1:1
	v_pk_mul_f32 v[2:3], v[8:9], v[12:13] op_sel_hi:[1,0]
	v_add_u32_e32 v4, 0x14a8, v44
	ds_write2_b32 v4, v2, v3 offset1:1
	s_waitcnt lgkmcnt(0)
	v_lshlrev_b32_e32 v74, 5, v42
	v_lshlrev_b32_e32 v20, 1, v13
	ds_read2_b32 v[6:7], v55 offset0:33 offset1:41
	ds_read2_b32 v[8:9], v55 offset1:8
	ds_read2_b32 v[10:11], v55 offset0:66 offset1:74
	ds_read2_b32 v[12:13], v55 offset0:99 offset1:107
	ds_read2_b32 v[42:43], v55 offset0:132 offset1:140
	ds_read2_b32 v[44:45], v55 offset0:165 offset1:173
	ds_read2_b32 v[66:67], v55 offset0:198 offset1:206
	ds_read2_b32 v[68:69], v55 offset0:231 offset1:239
	s_waitcnt lgkmcnt(6)
	v_cvt_pk_bf16_f32 v2, v8, v6
	v_or_b32_e32 v6, v74, v14
	v_lshl_add_u64 v[70:71], v[26:27], 0, v[20:21]
	v_lshlrev_b32_e32 v20, 11, v6
	s_waitcnt lgkmcnt(4)
	v_cvt_pk_bf16_f32 v3, v10, v12
	s_waitcnt lgkmcnt(2)
	v_cvt_pk_bf16_f32 v4, v42, v44
	s_waitcnt lgkmcnt(0)
	v_cvt_pk_bf16_f32 v5, v66, v68
	v_lshl_add_u64 v[72:73], v[70:71], 0, v[20:21]
	global_store_dwordx4 v[72:73], v[2:5], off sc1
	v_or_b32_e32 v6, v74, v17
	v_lshlrev_b32_e32 v20, 11, v6
	v_cvt_pk_bf16_f32 v2, v9, v7
	v_cvt_pk_bf16_f32 v3, v11, v13
	v_cvt_pk_bf16_f32 v4, v43, v45
	v_cvt_pk_bf16_f32 v5, v67, v69
	ds_read2_b32 v[8:9], v55 offset0:49 offset1:57
	ds_read2_b32 v[10:11], v55 offset0:16 offset1:24
	ds_read2_b32 v[12:13], v55 offset0:82 offset1:90
	ds_read2_b32 v[42:43], v55 offset0:115 offset1:123
	ds_read2_b32 v[44:45], v55 offset0:148 offset1:156
	ds_read2_b32 v[66:67], v55 offset0:181 offset1:189
	ds_read2_b32 v[68:69], v55 offset0:214 offset1:222
	ds_read2_b32 v[72:73], v55 offset0:247 offset1:255
	v_lshl_add_u64 v[6:7], v[70:71], 0, v[20:21]
	global_store_dwordx4 v[6:7], v[2:5], off sc1
	v_or_b32_e32 v6, v74, v47
	v_lshlrev_b32_e32 v20, 11, v6
	s_waitcnt lgkmcnt(6)
	v_cvt_pk_bf16_f32 v2, v10, v8
	s_waitcnt lgkmcnt(4)
	v_cvt_pk_bf16_f32 v3, v12, v42
	s_waitcnt lgkmcnt(2)
	v_cvt_pk_bf16_f32 v4, v44, v66
	s_waitcnt lgkmcnt(0)
	v_cvt_pk_bf16_f32 v5, v68, v72
	v_lshl_add_u64 v[6:7], v[70:71], 0, v[20:21]
	global_store_dwordx4 v[6:7], v[2:5], off sc1
	v_or_b32_e32 v6, v74, v49
	v_lshlrev_b32_e32 v20, 11, v6
	v_cvt_pk_bf16_f32 v2, v11, v9
	v_cvt_pk_bf16_f32 v3, v13, v43
	v_cvt_pk_bf16_f32 v4, v45, v67
	v_cvt_pk_bf16_f32 v5, v69, v73
	v_lshl_add_u64 v[6:7], v[70:71], 0, v[20:21]
	global_store_dwordx4 v[6:7], v[2:5], off sc1
	s_waitcnt lgkmcnt(0)
